# XCD barrier seams: non-leader workgroups issue their L1 invalidate before spinning on the release word (all other waves are parked, only sc1 polls in between) instead of after the release
# speedup vs baseline: 1.0036x; 1.0034x over previous
.LBB0_185:
	s_lshl_b32 s0, s81, 8
	s_add_u32 s0, s56, s0
	s_addc_u32 s1, s57, 0
	v_mov_b32_e32 v1, 0x1000
	v_mov_b32_e32 v3, 1
	global_atomic_add v3, v1, v3, s[0:1] offset:1024 sc0
	v_cvt_f32_u32_e32 v1, v2
	v_sub_u32_e32 v4, 0, v2
	v_rcp_iflag_f32_e32 v1, v1
	s_nop 0
	v_mul_f32_e32 v1, 0x4f7ffffe, v1
	v_cvt_u32_f32_e32 v1, v1
	v_mul_lo_u32 v4, v4, v1
	v_mul_hi_u32 v4, v1, v4
	v_add_u32_e32 v1, v1, v4
	s_waitcnt vmcnt(0)
	v_mul_hi_u32 v1, v3, v1
	v_mul_lo_u32 v4, v1, v2
	v_sub_u32_e32 v4, v3, v4
	v_add_u32_e32 v5, 1, v1
	v_cmp_ge_u32_e32 vcc, v4, v2
	v_add_u32_e32 v3, 1, v3
	s_nop 0
	v_cndmask_b32_e32 v1, v1, v5, vcc
	v_sub_u32_e32 v5, v4, v2
	v_cndmask_b32_e32 v4, v4, v5, vcc
	v_add_u32_e32 v5, 1, v1
	v_cmp_ge_u32_e32 vcc, v4, v2
	s_nop 1
	v_cndmask_b32_e32 v1, v1, v5, vcc
	v_mul_lo_u32 v4, v2, v1
	v_add_u32_e32 v2, v4, v2
	v_cmp_ne_u32_e32 vcc, v3, v2
	s_and_saveexec_b64 s[6:7], vcc
	s_xor_b64 s[6:7], exec, s[6:7]
	s_cbranch_execz .LBB0_199
	s_waitcnt lgkmcnt(0)
	buffer_inv sc1
	v_mov_b32_e32 v0, 0x2000
	global_load_dword v0, v0, s[0:1] offset:1024 sc1
	s_add_u32 s10, s0, 0x2400
	s_addc_u32 s11, s1, 0
	s_waitcnt vmcnt(0)
	v_cmp_eq_u32_e32 vcc, v0, v1
	s_and_saveexec_b64 s[8:9], vcc
	s_cbranch_execz .LBB0_198
	s_mov_b32 s24, 1
	s_mov_b64 s[12:13], 0
	v_mov_b32_e32 v0, 0
	s_branch .LBB0_189

.LBB0_198:
	s_or_b64 exec, exec, s[8:9]
	s_waitcnt vmcnt(0)
	s_nop 0
	s_waitcnt vmcnt(0)

.LBB0_278:
	s_lshl_b32 s4, s81, 8
	s_add_u32 s4, s56, s4
	s_addc_u32 s5, s57, 0
	v_mov_b32_e32 v1, 0x1000
	v_mov_b32_e32 v3, 1
	global_atomic_add v3, v1, v3, s[4:5] offset:1024 sc0
	v_cvt_f32_u32_e32 v1, v2
	v_sub_u32_e32 v4, 0, v2
	v_rcp_iflag_f32_e32 v1, v1
	s_nop 0
	v_mul_f32_e32 v1, 0x4f7ffffe, v1
	v_cvt_u32_f32_e32 v1, v1
	v_mul_lo_u32 v4, v4, v1
	v_mul_hi_u32 v4, v1, v4
	v_add_u32_e32 v1, v1, v4
	s_waitcnt vmcnt(0)
	v_mul_hi_u32 v1, v3, v1
	v_mul_lo_u32 v4, v1, v2
	v_sub_u32_e32 v4, v3, v4
	v_add_u32_e32 v5, 1, v1
	v_cmp_ge_u32_e32 vcc, v4, v2
	v_add_u32_e32 v3, 1, v3
	s_nop 0
	v_cndmask_b32_e32 v1, v1, v5, vcc
	v_sub_u32_e32 v5, v4, v2
	v_cndmask_b32_e32 v4, v4, v5, vcc
	v_add_u32_e32 v5, 1, v1
	v_cmp_ge_u32_e32 vcc, v4, v2
	s_nop 1
	v_cndmask_b32_e32 v1, v1, v5, vcc
	v_mul_lo_u32 v4, v2, v1
	v_add_u32_e32 v2, v4, v2
	v_cmp_ne_u32_e32 vcc, v3, v2
	s_and_saveexec_b64 s[6:7], vcc
	s_xor_b64 s[6:7], exec, s[6:7]
	s_cbranch_execz .LBB0_292
	s_waitcnt lgkmcnt(0)
	buffer_inv sc1
	v_mov_b32_e32 v0, 0x2000
	global_load_dword v0, v0, s[4:5] offset:1024 sc1
	s_add_u32 s10, s4, 0x2400
	s_addc_u32 s11, s5, 0
	s_waitcnt vmcnt(0)
	v_cmp_eq_u32_e32 vcc, v0, v1
	s_and_saveexec_b64 s[8:9], vcc
	s_cbranch_execz .LBB0_291
	s_mov_b32 s24, 1
	s_mov_b64 s[12:13], 0
	v_mov_b32_e32 v0, 0
	s_branch .LBB0_282

.LBB0_1381:
	s_lshl_b32 s4, s81, 8
	s_add_u32 s4, s56, s4
	s_addc_u32 s5, s57, 0
	v_mov_b32_e32 v1, 0x1000
	v_mov_b32_e32 v3, 1
	global_atomic_add v3, v1, v3, s[4:5] offset:1024 sc0
	v_cvt_f32_u32_e32 v1, v2
	v_sub_u32_e32 v4, 0, v2
	v_rcp_iflag_f32_e32 v1, v1
	s_nop 0
	v_mul_f32_e32 v1, 0x4f7ffffe, v1
	v_cvt_u32_f32_e32 v1, v1
	v_mul_lo_u32 v4, v4, v1
	v_mul_hi_u32 v4, v1, v4
	v_add_u32_e32 v1, v1, v4
	s_waitcnt vmcnt(0)
	v_mul_hi_u32 v1, v3, v1
	v_mul_lo_u32 v4, v1, v2
	v_sub_u32_e32 v4, v3, v4
	v_add_u32_e32 v5, 1, v1
	v_cmp_ge_u32_e32 vcc, v4, v2
	v_add_u32_e32 v3, 1, v3
	s_nop 0
	v_cndmask_b32_e32 v1, v1, v5, vcc
	v_sub_u32_e32 v5, v4, v2
	v_cndmask_b32_e32 v4, v4, v5, vcc
	v_add_u32_e32 v5, 1, v1
	v_cmp_ge_u32_e32 vcc, v4, v2
	s_nop 1
	v_cndmask_b32_e32 v1, v1, v5, vcc
	v_mul_lo_u32 v4, v2, v1
	v_add_u32_e32 v2, v4, v2
	v_cmp_ne_u32_e32 vcc, v3, v2
	s_and_saveexec_b64 s[8:9], vcc
	s_xor_b64 s[8:9], exec, s[8:9]
	s_cbranch_execz .LBB0_1395
	s_waitcnt lgkmcnt(0)
	buffer_inv sc1
	v_mov_b32_e32 v0, 0x2000
	global_load_dword v0, v0, s[4:5] offset:1024 sc1
	s_add_u32 s12, s4, 0x2400
	s_addc_u32 s13, s5, 0
	s_waitcnt vmcnt(0)
	v_cmp_eq_u32_e32 vcc, v0, v1
	s_and_saveexec_b64 s[10:11], vcc
	s_cbranch_execz .LBB0_1394
	s_mov_b32 s26, 1
	s_mov_b64 s[14:15], 0
	v_mov_b32_e32 v0, 0
	s_branch .LBB0_1385

.LBB0_1394:
	s_or_b64 exec, exec, s[10:11]
	s_waitcnt vmcnt(0)
	s_nop 0
	s_waitcnt vmcnt(0)

.LBB0_1836:
	s_lshl_b32 s4, s81, 8
	s_add_u32 s4, s56, s4
	s_addc_u32 s5, s57, 0
	v_mov_b32_e32 v1, 0x1000
	v_mov_b32_e32 v3, 1
	global_atomic_add v3, v1, v3, s[4:5] offset:1024 sc0
	v_cvt_f32_u32_e32 v1, v2
	v_sub_u32_e32 v4, 0, v2
	v_rcp_iflag_f32_e32 v1, v1
	s_nop 0
	v_mul_f32_e32 v1, 0x4f7ffffe, v1
	v_cvt_u32_f32_e32 v1, v1
	v_mul_lo_u32 v4, v4, v1
	v_mul_hi_u32 v4, v1, v4
	v_add_u32_e32 v1, v1, v4
	s_waitcnt vmcnt(0)
	v_mul_hi_u32 v1, v3, v1
	v_mul_lo_u32 v4, v1, v2
	v_sub_u32_e32 v4, v3, v4
	v_add_u32_e32 v5, 1, v1
	v_cmp_ge_u32_e32 vcc, v4, v2
	v_add_u32_e32 v3, 1, v3
	s_nop 0
	v_cndmask_b32_e32 v1, v1, v5, vcc
	v_sub_u32_e32 v5, v4, v2
	v_cndmask_b32_e32 v4, v4, v5, vcc
	v_add_u32_e32 v5, 1, v1
	v_cmp_ge_u32_e32 vcc, v4, v2
	s_nop 1
	v_cndmask_b32_e32 v1, v1, v5, vcc
	v_mul_lo_u32 v4, v2, v1
	v_add_u32_e32 v2, v4, v2
	v_cmp_ne_u32_e32 vcc, v3, v2
	s_and_saveexec_b64 s[6:7], vcc
	s_xor_b64 s[6:7], exec, s[6:7]
	s_cbranch_execz .LBB0_1850
	s_waitcnt lgkmcnt(0)
	buffer_inv sc1
	v_mov_b32_e32 v0, 0x2000
	global_load_dword v0, v0, s[4:5] offset:1024 sc1
	s_add_u32 s10, s4, 0x2400
	s_addc_u32 s11, s5, 0
	s_waitcnt vmcnt(0)
	v_cmp_eq_u32_e32 vcc, v0, v1
	s_and_saveexec_b64 s[8:9], vcc
	s_cbranch_execz .LBB0_1849
	s_mov_b32 s22, 1
	s_mov_b64 s[12:13], 0
	v_mov_b32_e32 v0, 0
	s_branch .LBB0_1840
